# plus static s_setprio 1 for RWKV producer waves (younger half) during the tile loop
# speedup vs baseline: 1.0192x; 1.0042x over previous
.LBB0_572:
	s_andn2_saveexec_b64 s[0:1], s[6:7]
	v_or_b32_e32 v40, 1, v84
	v_or_b32_e32 v41, 2, v84
	v_or_b32_e32 v42, 3, v84
	v_or_b32_e32 v85, v37, v76
	v_lshl_or_b32 v86, v40, 6, v76
	v_lshl_or_b32 v87, v41, 6, v76
	v_lshl_or_b32 v88, v42, 6, v76
	s_or_b64 exec, exec, s[0:1]
	s_movk_i32 s0, 0xc0
	v_and_or_b32 v90, v30, s0, v37
	v_or_b32_e32 v37, v84, v29
	v_or_b32_e32 v30, 16, v39
	v_mul_u32_u24_e32 v93, 0x44, v37
	v_readlane_b32 s16, v253, 18
	v_readlane_b32 s1, v253, 17
	v_lshlrev_b32_e32 v43, 5, v30
	v_lshl_add_u32 v44, v93, 2, s16
	v_add_u32_e32 v92, s1, v43
	v_add3_u32 v94, v44, v43, s94
	v_lshlrev_b32_e32 v95, 6, v37
	v_or_b32_e32 v37, 32, v39
	s_ashr_i32 s3, s2, 31
	v_and_b32_e32 v43, 56, v83
	v_lshl_add_u32 v89, v39, 5, s1
	v_lshlrev_b32_e32 v91, 3, v30
	v_lshl_add_u32 v96, v37, 5, s1
	s_lshl_b64 s[0:1], s[2:3], 11
	v_or_b32_e32 v44, s24, v43
	v_lshrrev_b32_e32 v28, 2, v28
	v_lshl_or_b32 v36, v77, 6, v36
	v_or_b32_e32 v52, s0, v84
	v_or_b32_e32 v44, 0x900, v44
	v_add_u32_e32 v45, 0x940, v91
	v_cmp_gt_u32_e32 vcc, 24, v30
	s_add_i32 s0, s24, 0x940
	v_and_b32_e32 v98, 62, v28
	v_add_lshl_u32 v28, v2, v35, 2
	v_lshl_or_b32 v35, v35, 8, v36
	v_readlane_b32 s17, v253, 19
	v_cmp_lt_u32_e64 s[8:9], 23, v30
	v_mov_b32_e32 v53, s1
	v_cndmask_b32_e32 v30, v45, v44, vcc
	v_mov_b32_e32 v44, s0
	v_add_u32_e32 v100, s16, v28
	s_add_i32 s0, 0, 0x10100
	v_add_u32_e32 v102, s17, v28
	s_add_i32 s1, 0, 0x14100
	v_or_b32_e32 v28, 0x100, v35
	v_add_u32_e32 v104, s0, v28
	v_add_u32_e32 v105, s1, v28
	v_or_b32_e32 v28, 0x200, v35
	v_add_u32_e32 v107, s0, v28
	v_add_u32_e32 v108, s1, v28
	v_or_b32_e32 v28, 0x300, v35
	v_add_u32_e32 v109, s0, v28
	v_add_u32_e32 v110, s1, v28
	v_add_lshl_u32 v28, v34, v2, 2
	v_add_u32_e32 v111, s16, v28
	v_add_u32_e32 v113, s17, v28
	v_or_b32_e32 v28, 0x500, v35
	v_add_u32_e32 v115, s0, v28
	v_add_u32_e32 v116, s1, v28
	v_or_b32_e32 v28, 0x600, v35
	v_add_u32_e32 v117, s0, v28
	v_add_u32_e32 v118, s1, v28
	v_or_b32_e32 v28, 0x700, v35
	v_add_u32_e32 v119, s0, v28
	v_add_u32_e32 v120, s1, v28
	v_add_lshl_u32 v28, v33, v2, 2
	v_add_u32_e32 v121, s16, v28
	v_add_u32_e32 v123, s17, v28
	v_or_b32_e32 v28, 0x900, v35
	v_add_u32_e32 v125, s0, v28
	v_add_u32_e32 v126, s1, v28
	v_or_b32_e32 v28, 0xa00, v35
	v_add_u32_e32 v127, s0, v28
	v_add_u32_e32 v128, s1, v28
	v_or_b32_e32 v28, 0xb00, v35
	v_add_u32_e32 v129, s0, v28
	v_add_u32_e32 v130, s1, v28
	v_add_lshl_u32 v28, v32, v2, 2
	v_add_u32_e32 v131, s16, v28
	v_add_u32_e32 v133, s17, v28
	v_or_b32_e32 v28, 0xd00, v35
	v_lshl_or_b32 v34, v34, 8, v36
	v_lshl_or_b32 v33, v33, 8, v36
	v_lshl_or_b32 v32, v32, 8, v36
	v_add_u32_e32 v135, s0, v28
	v_add_u32_e32 v136, s1, v28
	v_or_b32_e32 v28, 0xe00, v35
	v_add_lshl_u32 v2, v3, v2, 2
	v_lshl_or_b32 v3, v3, 8, v36
	v_add_u32_e32 v101, s0, v35
	v_add_u32_e32 v112, s0, v34
	v_add_u32_e32 v122, s0, v33
	v_add_u32_e32 v132, s0, v32
	v_add_u32_e32 v137, s0, v28
	v_add_u32_e32 v140, s0, v3
	s_add_i32 s0, 0, 0x10000
	v_and_b32_e32 v1, 0xc00, v1
	v_add_u32_e32 v103, s1, v35
	v_add_u32_e32 v114, s1, v34
	v_add_u32_e32 v124, s1, v33
	v_add_u32_e32 v134, s1, v32
	v_add_u32_e32 v138, s1, v28
	v_add_u32_e32 v139, s16, v2
	v_add_u32_e32 v141, s17, v2
	v_add_u32_e32 v142, s1, v3
	v_lshl_add_u32 v106, v84, 2, s0
	v_lshl_add_u32 v144, v40, 2, s0
	v_lshl_add_u32 v145, v41, 2, s0
	v_lshl_add_u32 v146, v42, 2, s0
	v_add3_u32 v147, 0, v36, v1
	s_mul_hi_i32 s0, s2, 0xf00000
	s_mul_i32 s1, s2, 0xf00000
	v_mul_hi_u32_u24_e32 v1, 0x7800, v77
	v_mul_u32_u24_e32 v2, 0x7800, v77
	v_or_b32_e32 v3, s0, v1
	v_or_b32_e32 v2, s1, v2
	s_movk_i32 s0, 0x1e00
	v_or_b32_e32 v1, s24, v38
	v_mad_u64_u32 v[2:3], s[0:1], v29, s0, v[2:3]
	v_add_lshl_u32 v28, v1, v43, 1
	v_mov_b32_e32 v29, v0
	v_lshl_add_u64 v[28:29], v[2:3], 0, v[28:29]
	v_cmp_gt_u32_e64 s[6:7], 8, v39
	v_cmp_lt_u32_e64 s[10:11], 39, v37
	v_lshlrev_b32_e32 v39, 3, v37
	v_cmp_gt_u32_e64 s[12:13], 40, v37
	v_mov_b32_e32 v37, 0x940
	v_lshl_add_u64 v[54:55], s[58:59], 0, v[28:29]
	v_lshlrev_b32_e32 v28, 1, v30
	v_mov_b32_e32 v29, v0
	v_cndmask_b32_e64 v37, v44, v37, s[12:13]
	v_lshl_add_u64 v[28:29], v[2:3], 0, v[28:29]
	v_lshl_add_u64 v[56:57], s[58:59], 0, v[28:29]
	v_add_u32_e32 v1, v37, v83
	v_mov_b32_e32 v28, 0x200
	v_lshl_add_u32 v28, v1, 1, v28
	v_mov_b32_e32 v29, v0
	v_lshl_add_u64 v[2:3], v[2:3], 0, v[28:29]
	v_mov_b32_e32 v1, v0
	v_lshlrev_b32_e32 v97, 3, v31
	s_mov_b32 s25, 0
	v_cmp_eq_u32_e64 s[14:15], 0, v31
	v_lshl_add_u32 v99, v98, 2, 0
	v_lshl_add_u32 v143, v31, 5, 0
	v_cmp_eq_u32_e64 s[16:17], 0, v76
	v_mov_b32_e32 v49, v48
	v_mov_b32_e32 v51, v50
	v_lshl_add_u64 v[58:59], s[58:59], 0, v[2:3]
	s_mov_b32 s88, -16
	s_mov_b64 s[18:19], 0
	v_lshlrev_b32_e32 v148, 2, v39
	v_mov_b64_e32 v[44:45], v[0:1]
	v_mov_b64_e32 v[46:47], v[0:1]
	v_mov_b64_e32 v[60:61], v[0:1]
	v_mov_b64_e32 v[62:63], v[0:1]
	v_mov_b64_e32 v[64:65], v[0:1]
	v_mov_b64_e32 v[66:67], v[0:1]
	v_mov_b64_e32 v[68:69], v[0:1]
	v_mov_b64_e32 v[70:71], v[0:1]
	s_waitcnt lgkmcnt(0)
	s_barrier
	s_cmp_eq_u64 s[4:5], 0
	s_cbranch_scc1 .Lrw_prio_skip
	s_setprio 1
.Lrw_prio_skip:
	s_branch .LBB0_577
.LBB0_575:
	s_or_b64 exec, exec, s[20:21]

.LBB0_646:
	s_setprio 0
	s_and_saveexec_b64 s[0:1], s[4:5]
	s_cbranch_execz .LBB0_648
	s_waitcnt vmcnt(2)
	v_lshl_add_u32 v8, v85, 2, 0
	ds_read2st64_b32 v[6:7], v8 offset0:208 offset1:209
	v_mov_b32_e32 v2, v0
	v_mov_b32_e32 v3, v0
	s_movk_i32 s5, 0x7fff
	s_lshl_b64 s[2:3], s[2:3], 22
	s_waitcnt lgkmcnt(0)
	v_add_f32_dpp v1, v6, v6 quad_perm:[1,0,3,2] row_mask:0xf bank_mask:0xf bound_ctrl:1
	s_add_u32 s2, s62, s2
	s_addc_u32 s3, s63, s3
	v_add_f32_dpp v1, v1, v1 quad_perm:[2,3,0,1] row_mask:0xf bank_mask:0xf bound_ctrl:1
	s_lshl_b32 s88, s24, 1
	s_nop 0
	v_add_f32_dpp v1, v1, v1 row_half_mirror row_mask:0xf bank_mask:0xf bound_ctrl:1
	s_nop 1
	v_add_f32_dpp v1, v1, v1 row_mirror row_mask:0xf bank_mask:0xf bound_ctrl:1
	s_nop 1
	v_mov_b32_dpp v2, v1 row_bcast:15 row_mask:0xa bank_mask:0xf
	v_add_f32_e32 v1, v1, v2
	v_mov_b32_e32 v2, v0
	s_nop 1
	v_mov_b32_dpp v2, v1 row_bcast:31 row_mask:0xc bank_mask:0xf
	v_add_f32_e32 v1, v1, v2
	s_nop 0
	v_readlane_b32 s4, v1, 63
	s_nop 1
	v_fma_f32 v1, s4, v191, v6
	v_mul_f32_e32 v2, v1, v1
	v_mov_b32_e32 v6, v0
	s_nop 0
	v_mov_b32_dpp v2, v2 quad_perm:[1,0,3,2] row_mask:0xf bank_mask:0xf bound_ctrl:1
	v_fmac_f32_e32 v2, v1, v1
	s_nop 1
	v_add_f32_dpp v2, v2, v2 quad_perm:[2,3,0,1] row_mask:0xf bank_mask:0xf bound_ctrl:1
	s_nop 1
	v_add_f32_dpp v2, v2, v2 row_half_mirror row_mask:0xf bank_mask:0xf bound_ctrl:1
	s_nop 1
	v_add_f32_dpp v2, v2, v2 row_mirror row_mask:0xf bank_mask:0xf bound_ctrl:1
	s_nop 1
	v_mov_b32_dpp v3, v2 row_bcast:15 row_mask:0xa bank_mask:0xf
	v_add_f32_e32 v2, v2, v3
	v_mov_b32_e32 v3, v0
	s_nop 1
	v_mov_b32_dpp v3, v2 row_bcast:31 row_mask:0xc bank_mask:0xf
	v_add_f32_e32 v2, v2, v3
	s_nop 0
	v_readlane_b32 s4, v2, 63
	s_nop 1
	v_fma_f32 v2, s4, v196, v183
	v_cmp_gt_f32_e32 vcc, s72, v2
	v_mul_f32_e32 v3, 0x4b800000, v2
	s_nop 0
	v_cndmask_b32_e32 v2, v2, v3, vcc
	v_rsq_f32_e32 v2, v2
	s_nop 0
	v_mul_f32_e32 v3, 0x45800000, v2
	v_cndmask_b32_e32 v2, v2, v3, vcc
	v_mul_f32_e32 v1, v1, v2
	ds_read_b128 v[2:5], v106 offset:64
	ds_read2st64_b32 v[10:11], v8 offset0:176 offset1:177
	ds_read2st64_b32 v[12:13], v8 offset0:240 offset1:241
	v_fma_f32 v1, v50, v1, v48
	s_waitcnt lgkmcnt(1)
	v_fmac_f32_e32 v1, v2, v10
	s_waitcnt lgkmcnt(0)
	v_mul_f32_e32 v2, 0xbfb8aa3b, v12
	v_exp_f32_e32 v2, v2
	s_nop 0
	v_add_f32_e32 v2, 1.0, v2
	v_rcp_f32_e32 v2, v2
	s_nop 0
	v_mul_f32_e32 v2, v12, v2
	v_mul_f32_e32 v1, v2, v1
	v_bfe_u32 v2, v1, 16, 1
	v_add3_u32 v1, v1, v2, s5
	s_nop 0
	v_add_f32_dpp v2, v7, v7 quad_perm:[1,0,3,2] row_mask:0xf bank_mask:0xf bound_ctrl:1
	s_nop 1
	v_add_f32_dpp v2, v2, v2 quad_perm:[2,3,0,1] row_mask:0xf bank_mask:0xf bound_ctrl:1
	s_nop 1
	v_add_f32_dpp v2, v2, v2 row_half_mirror row_mask:0xf bank_mask:0xf bound_ctrl:1
	s_nop 1
	v_add_f32_dpp v2, v2, v2 row_mirror row_mask:0xf bank_mask:0xf bound_ctrl:1
	s_nop 1
	v_mov_b32_dpp v6, v2 row_bcast:15 row_mask:0xa bank_mask:0xf
	v_add_f32_e32 v2, v2, v6
	v_mov_b32_e32 v6, v0
	s_nop 1
	v_mov_b32_dpp v6, v2 row_bcast:31 row_mask:0xc bank_mask:0xf
	v_add_f32_e32 v2, v2, v6
	v_mov_b32_e32 v6, v0
	v_readlane_b32 s4, v2, 63
	s_nop 1
	v_fmac_f32_e32 v7, s4, v191
	v_mul_f32_e32 v2, v7, v7
	s_nop 1
	v_mov_b32_dpp v2, v2 quad_perm:[1,0,3,2] row_mask:0xf bank_mask:0xf bound_ctrl:1
	v_fmac_f32_e32 v2, v7, v7
	s_nop 1
	v_add_f32_dpp v2, v2, v2 quad_perm:[2,3,0,1] row_mask:0xf bank_mask:0xf bound_ctrl:1
	s_nop 1
	v_add_f32_dpp v2, v2, v2 row_half_mirror row_mask:0xf bank_mask:0xf bound_ctrl:1
	s_nop 1
	v_add_f32_dpp v2, v2, v2 row_mirror row_mask:0xf bank_mask:0xf bound_ctrl:1
	s_nop 1
	v_mov_b32_dpp v6, v2 row_bcast:15 row_mask:0xa bank_mask:0xf
	v_add_f32_e32 v2, v2, v6
	v_mov_b32_e32 v6, v0
	s_nop 1
	v_mov_b32_dpp v6, v2 row_bcast:31 row_mask:0xc bank_mask:0xf
	v_add_f32_e32 v2, v2, v6
	s_nop 0
	v_readlane_b32 s4, v2, 63
	s_nop 1
	v_fma_f32 v2, s4, v196, v183
	v_cmp_gt_f32_e32 vcc, s72, v2
	v_mul_f32_e32 v6, 0x4b800000, v2
	s_nop 0
	v_cndmask_b32_e32 v2, v2, v6, vcc
	v_rsq_f32_e32 v2, v2
	s_nop 0
	v_mul_f32_e32 v6, 0x45800000, v2
	v_cndmask_b32_e32 v2, v2, v6, vcc
	v_mul_f32_e32 v2, v7, v2
	v_fma_f32 v2, v50, v2, v48
	v_fmac_f32_e32 v2, v3, v11
	v_mul_f32_e32 v3, 0xbfb8aa3b, v13
	v_exp_f32_e32 v3, v3
	v_mov_b32_e32 v7, v0
	v_add_f32_e32 v3, 1.0, v3
	v_rcp_f32_e32 v3, v3
	s_nop 0
	v_mul_f32_e32 v3, v13, v3
	v_mul_f32_e32 v2, v3, v2
	v_bfe_u32 v3, v2, 16, 1
	v_add3_u32 v10, v2, v3, s5
	ds_read2st64_b32 v[2:3], v8 offset0:210 offset1:211
	s_waitcnt lgkmcnt(0)
	s_nop 0
	v_add_f32_dpp v6, v2, v2 quad_perm:[1,0,3,2] row_mask:0xf bank_mask:0xf bound_ctrl:1
	s_nop 1
	v_add_f32_dpp v6, v6, v6 quad_perm:[2,3,0,1] row_mask:0xf bank_mask:0xf bound_ctrl:1
	s_nop 1
	v_add_f32_dpp v6, v6, v6 row_half_mirror row_mask:0xf bank_mask:0xf bound_ctrl:1
	s_nop 1
	v_add_f32_dpp v6, v6, v6 row_mirror row_mask:0xf bank_mask:0xf bound_ctrl:1
	s_nop 1
	v_mov_b32_dpp v7, v6 row_bcast:15 row_mask:0xa bank_mask:0xf
	v_add_f32_e32 v6, v6, v7
	v_mov_b32_e32 v7, v0
	s_nop 1
	v_mov_b32_dpp v7, v6 row_bcast:31 row_mask:0xc bank_mask:0xf
	v_add_f32_e32 v6, v6, v7
	v_mov_b32_e32 v7, v0
	v_readlane_b32 s4, v6, 63
	s_nop 1
	v_fma_f32 v2, s4, v191, v2
	v_mul_f32_e32 v6, v2, v2
	s_nop 1
	v_mov_b32_dpp v6, v6 quad_perm:[1,0,3,2] row_mask:0xf bank_mask:0xf bound_ctrl:1
	v_fmac_f32_e32 v6, v2, v2
	s_nop 1
	v_add_f32_dpp v6, v6, v6 quad_perm:[2,3,0,1] row_mask:0xf bank_mask:0xf bound_ctrl:1
	s_nop 1
	v_add_f32_dpp v6, v6, v6 row_half_mirror row_mask:0xf bank_mask:0xf bound_ctrl:1
	s_nop 1
	v_add_f32_dpp v6, v6, v6 row_mirror row_mask:0xf bank_mask:0xf bound_ctrl:1
	s_nop 1
	v_mov_b32_dpp v7, v6 row_bcast:15 row_mask:0xa bank_mask:0xf
	v_add_f32_e32 v6, v6, v7
	v_mov_b32_e32 v7, v0
	s_nop 1
	v_mov_b32_dpp v7, v6 row_bcast:31 row_mask:0xc bank_mask:0xf
	v_add_f32_e32 v6, v6, v7
	s_nop 0
	v_readlane_b32 s4, v6, 63
	s_nop 1
	v_fma_f32 v6, s4, v196, v183
	v_cmp_gt_f32_e32 vcc, s72, v6
	v_mul_f32_e32 v7, 0x4b800000, v6
	s_nop 0
	v_cndmask_b32_e32 v6, v6, v7, vcc
	v_rsq_f32_e32 v6, v6
	s_nop 0
	v_mul_f32_e32 v7, 0x45800000, v6
	v_cndmask_b32_e32 v6, v6, v7, vcc
	v_mul_f32_e32 v2, v2, v6
	ds_read2st64_b32 v[6:7], v8 offset0:178 offset1:179
	ds_read2st64_b32 v[8:9], v8 offset0:242 offset1:243
	v_fma_f32 v2, v50, v2, v48
	s_waitcnt lgkmcnt(1)
	v_fmac_f32_e32 v2, v4, v6
	s_waitcnt lgkmcnt(0)
	v_mul_f32_e32 v4, 0xbfb8aa3b, v8
	v_exp_f32_e32 v4, v4
	s_nop 0
	v_add_f32_e32 v4, 1.0, v4
	v_rcp_f32_e32 v4, v4
	s_nop 0
	v_mul_f32_e32 v4, v8, v4
	v_mul_f32_e32 v2, v4, v2
	v_bfe_u32 v4, v2, 16, 1
	v_add3_u32 v6, v2, v4, s5
	v_add_f32_dpp v2, v3, v3 quad_perm:[1,0,3,2] row_mask:0xf bank_mask:0xf bound_ctrl:1
	v_mov_b32_e32 v4, v0
	s_nop 0
	v_add_f32_dpp v2, v2, v2 quad_perm:[2,3,0,1] row_mask:0xf bank_mask:0xf bound_ctrl:1
	s_nop 1
	v_add_f32_dpp v2, v2, v2 row_half_mirror row_mask:0xf bank_mask:0xf bound_ctrl:1
	s_nop 1
	v_add_f32_dpp v2, v2, v2 row_mirror row_mask:0xf bank_mask:0xf bound_ctrl:1
	s_nop 1
	v_mov_b32_dpp v4, v2 row_bcast:15 row_mask:0xa bank_mask:0xf
	v_add_f32_e32 v2, v2, v4
	v_mov_b32_e32 v4, v0
	s_nop 1
	v_mov_b32_dpp v4, v2 row_bcast:31 row_mask:0xc bank_mask:0xf
	v_add_f32_e32 v2, v2, v4
	v_mov_b32_e32 v4, v0
	v_readlane_b32 s4, v2, 63
	s_nop 1
	v_fmac_f32_e32 v3, s4, v191
	v_mul_f32_e32 v2, v3, v3
	s_nop 1
	v_mov_b32_dpp v2, v2 quad_perm:[1,0,3,2] row_mask:0xf bank_mask:0xf bound_ctrl:1
	v_fmac_f32_e32 v2, v3, v3
	s_nop 1
	v_add_f32_dpp v2, v2, v2 quad_perm:[2,3,0,1] row_mask:0xf bank_mask:0xf bound_ctrl:1
	s_nop 1
	v_add_f32_dpp v2, v2, v2 row_half_mirror row_mask:0xf bank_mask:0xf bound_ctrl:1
	s_nop 1
	v_add_f32_dpp v2, v2, v2 row_mirror row_mask:0xf bank_mask:0xf bound_ctrl:1
	s_nop 1
	v_mov_b32_dpp v4, v2 row_bcast:15 row_mask:0xa bank_mask:0xf
	v_add_f32_e32 v2, v2, v4
	v_mov_b32_e32 v4, v0
	s_nop 1
	v_mov_b32_dpp v4, v2 row_bcast:31 row_mask:0xc bank_mask:0xf
	v_add_f32_e32 v2, v2, v4
	s_nop 0
	v_readlane_b32 s4, v2, 63
	s_nop 1
	v_fma_f32 v2, s4, v196, v183
	v_cmp_gt_f32_e32 vcc, s72, v2
	v_mul_f32_e32 v4, 0x4b800000, v2
	s_nop 0
	v_cndmask_b32_e32 v2, v2, v4, vcc
	v_rsq_f32_e32 v2, v2
	s_nop 0
	v_mul_f32_e32 v4, 0x45800000, v2
	v_cndmask_b32_e32 v2, v2, v4, vcc
	v_mul_f32_e32 v2, v3, v2
	v_fmac_f32_e32 v48, v50, v2
	v_mul_f32_e32 v2, 0xbfb8aa3b, v9
	v_exp_f32_e32 v2, v2
	v_fmac_f32_e32 v48, v5, v7
	v_lshlrev_b32_e32 v4, 1, v76
	v_mov_b32_e32 v5, v0
	v_add_f32_e32 v2, 1.0, v2
	v_rcp_f32_e32 v2, v2
	s_nop 0
	v_mul_f32_e32 v2, v9, v2
	v_mul_f32_e32 v2, v2, v48
	v_bfe_u32 v3, v2, 16, 1
	v_add3_u32 v7, v2, v3, s5
	v_lshlrev_b32_e32 v2, 13, v77
	v_mov_b32_e32 v3, v0
	v_lshl_add_u64 v[2:3], s[2:3], 0, v[2:3]
	v_lshl_add_u64 v[2:3], v[2:3], 0, s[88:89]
	v_lshl_add_u64 v[2:3], v[2:3], 0, v[4:5]
	v_add_co_u32_e32 v4, vcc, 0x3f8000, v2
	s_nop 1
	v_addc_co_u32_e32 v5, vcc, 0, v3, vcc
	v_add_co_u32_e32 v2, vcc, 0x3f9000, v2
	global_store_short_d16_hi v[4:5], v1, off offset:1024
	global_store_short_d16_hi v[4:5], v10, off offset:3072
	v_addc_co_u32_e32 v3, vcc, 0, v3, vcc
	global_store_short_d16_hi v[2:3], v6, off offset:1024
	global_store_short_d16_hi v[2:3], v7, off offset:3072
